# v29 + LayerNorm next-row prefetch loads with the nt (streaming) cache hint
# speedup vs baseline: 1.0071x; 1.0071x over previous
; DI void lnmod_phase(const Args& A, LAS unsigned char* lds, int tid, int bid, int G, bool init, int l_norm, int i_norm, int l_mod, int i_mod, bool want_dt, int nrows, bool ctx_partial, const float* gprev, const float* bprev) {
;     ...
;         { const int rown = row + G * 8;
;           if (rown < nrows) {
;               if (init) { const float* xin = rown < M_LAT ? A.in[I_X] + (size_t)rown * DM : A.in[I_CTX] + (size_t)(rown - M_LAT) * DM;
; #pragma unroll
;                   for (int j = 0; j < 4; ++j) fn[j] = *(const f32x4*)(xin + 256 * j + 4 * lane); }
;               else {
; #pragma unroll
;                   for (int j = 0; j < 4; ++j) un[j] = *(const u32x2*)(X16 + (size_t)rown * DM + 256 * j + 4 * lane); } } }
.LBB0_205:
	v_add_u32_e32 v116, s18, v86
	s_mov_b32 s4, 0x8800
	v_cmp_gt_i32_e32 vcc, s4, v116
	s_mov_b32 s4, 0x87ff
	v_cmp_lt_i32_e64 s[4:5], s4, v116
	v_mov_b32_e32 v78, v92
	v_mov_b32_e32 v79, v93
	v_mov_b32_e32 v80, v94
	v_mov_b32_e32 v81, v95
	v_mov_b32_e32 v82, v98
	v_mov_b32_e32 v83, v99
	v_mov_b32_e32 v84, v88
	v_mov_b32_e32 v85, v89
	s_and_saveexec_b64 s[6:7], vcc
	s_cbranch_execz .LBB0_207
	v_readlane_b32 s36, v253, 23
	v_readlane_b32 s38, v253, 25
	v_readlane_b32 s39, v253, 26
	v_readlane_b32 s37, v253, 24
	s_nop 0
	v_lshl_add_u64 v[78:79], s[38:39], 0, v[72:73]
	v_add_co_u32_e32 v84, vcc, 0x21200000, v78
	s_nop 1
	v_addc_co_u32_e32 v85, vcc, 0, v79, vcc
	global_load_dwordx2 v[78:79], v[84:85], off nt
	global_load_dwordx2 v[80:81], v[84:85], off offset:512 nt
	global_load_dwordx2 v[82:83], v[84:85], off offset:1024 nt
	s_nop 0
	global_load_dwordx2 v[84:85], v[84:85], off offset:1536 nt

; DI void lnmod_phase(const Args& A, LAS unsigned char* lds, int tid, int bid, int G, bool init, int l_norm, int i_norm, int l_mod, int i_mod, bool want_dt, int nrows, bool ctx_partial, const float* gprev, const float* bprev) {
;     ...
;         { const int rown = row + G * 8;
;           if (rown < nrows) {
;               if (init) { const float* xin = rown < M_LAT ? A.in[I_X] + (size_t)rown * DM : A.in[I_CTX] + (size_t)(rown - M_LAT) * DM;
; #pragma unroll
;                   for (int j = 0; j < 4; ++j) fn[j] = *(const f32x4*)(xin + 256 * j + 4 * lane); }
;               else {
; #pragma unroll
;                   for (int j = 0; j < 4; ++j) un[j] = *(const u32x2*)(X16 + (size_t)rown * DM + 256 * j + 4 * lane); } } }
.LBB0_229:
	v_add_u32_e32 v81, s14, v118
	v_readlane_b32 s0, v253, 39
	v_mov_b32_e32 v96, v66
	v_mov_b32_e32 v97, v67
	v_cmp_gt_i32_e32 vcc, s0, v81
	v_cmp_le_i32_e64 s[0:1], s0, v81
	v_mov_b32_e32 v98, v72
	v_mov_b32_e32 v99, v73
	v_mov_b32_e32 v100, v70
	v_mov_b32_e32 v101, v71
	v_mov_b32_e32 v102, v76
	v_mov_b32_e32 v103, v77
	s_and_saveexec_b64 s[4:5], vcc
	s_cbranch_execz .LBB0_231
	v_readlane_b32 s36, v253, 23
	v_readlane_b32 s38, v253, 25
	v_readlane_b32 s39, v253, 26
	v_readlane_b32 s37, v253, 24
	s_nop 0
	v_lshl_add_u64 v[64:65], s[38:39], 0, v[90:91]
	v_add_co_u32_e32 v64, vcc, 0x21200000, v64
	s_nop 1
	v_addc_co_u32_e32 v65, vcc, 0, v65, vcc
	global_load_dwordx2 v[96:97], v[64:65], off nt
	global_load_dwordx2 v[98:99], v[64:65], off offset:512 nt
	global_load_dwordx2 v[100:101], v[64:65], off offset:1024 nt
	global_load_dwordx2 v[102:103], v[64:65], off offset:1536 nt

; DI void lnmod_phase(const Args& A, LAS unsigned char* lds, int tid, int bid, int G, bool init, int l_norm, int i_norm, int l_mod, int i_mod, bool want_dt, int nrows, bool ctx_partial, const float* gprev, const float* bprev) {
;     ...
;         { const int rown = row + G * 8;
;           if (rown < nrows) {
;               if (init) { const float* xin = rown < M_LAT ? A.in[I_X] + (size_t)rown * DM : A.in[I_CTX] + (size_t)(rown - M_LAT) * DM;
; #pragma unroll
;                   for (int j = 0; j < 4; ++j) fn[j] = *(const f32x4*)(xin + 256 * j + 4 * lane); }
;               else {
; #pragma unroll
;                   for (int j = 0; j < 4; ++j) un[j] = *(const u32x2*)(X16 + (size_t)rown * DM + 256 * j + 4 * lane); } } }
.LBB0_280:
	v_add_u32_e32 v67, s8, v84
	v_readlane_b32 s0, v253, 39
	v_mov_b32_e32 v76, v90
	v_mov_b32_e32 v77, v91
	v_cmp_gt_i32_e32 vcc, s0, v67
	v_cmp_le_i32_e64 s[0:1], s0, v67
	v_mov_b32_e32 v78, v92
	v_mov_b32_e32 v79, v93
	v_mov_b32_e32 v80, v96
	v_mov_b32_e32 v81, v97
	v_mov_b32_e32 v82, v86
	v_mov_b32_e32 v83, v87
	s_and_saveexec_b64 s[4:5], vcc
	s_cbranch_execz .LBB0_282
	v_readlane_b32 s24, v253, 23
	v_readlane_b32 s26, v253, 25
	v_readlane_b32 s27, v253, 26
	v_readlane_b32 s25, v253, 24
	s_nop 0
	v_lshl_add_u64 v[76:77], s[26:27], 0, v[72:73]
	v_add_co_u32_e32 v82, vcc, 0x21200000, v76
	s_nop 1
	v_addc_co_u32_e32 v83, vcc, 0, v77, vcc
	global_load_dwordx2 v[76:77], v[82:83], off nt
	global_load_dwordx2 v[78:79], v[82:83], off offset:512 nt
	global_load_dwordx2 v[80:81], v[82:83], off offset:1024 nt
	s_nop 0
	global_load_dwordx2 v[82:83], v[82:83], off offset:1536 nt
